# baseline (speedup 1.0000x reference)
.LBB0_252:
	s_or_b64 exec, exec, s[46:47]
	v_and_b32_e32 v131, 15, v204
	v_lshlrev_b32_e32 v4, 2, v204
	v_and_b32_e32 v2, 48, v204
	v_lshlrev_b32_e32 v3, 6, v131
	v_and_b32_e32 v4, 32, v4
	v_bitop3_b32 v238, v2, v4, v3 bitop3:0x36
	v_lshlrev_b32_e32 v2, 13, v130
	v_add3_u32 v237, 0, v2, v238
	v_lshlrev_b32_e32 v2, 6, v204
	v_and_b32_e32 v2, 0x3000, v2
	s_add_i32 s2, 0, 0x10000
	v_add_u32_e32 v239, s2, v2
	s_lshr_b32 s2, s31, 26
	s_add_i32 s2, s30, s2
	v_add_u32_e32 v242, 0x18000, v232
	s_ashr_i32 s33, s2, 6
	v_readfirstlane_b32 s2, v242
	v_add_u32_e32 v243, 0x1a000, v232
	s_mov_b32 s46, s26
	s_mov_b32 s47, s27
	s_mov_b32 m0, s2
	v_readfirstlane_b32 s31, v243
	v_add_u32_e32 v244, 0x8000, v232
	s_waitcnt vmcnt(0)
	s_barrier
	buffer_load_dwordx4 v0, s[44:47], s17 offen lds
	s_add_i32 s2, s8, 0x80
	s_mov_b32 m0, s31
	v_readfirstlane_b32 s31, v244
	v_add_u32_e32 v245, 0xa000, v232
	buffer_load_dwordx4 v0, s[44:47], s2 offen lds
	s_mov_b32 m0, s31
	v_readfirstlane_b32 s31, v245
	v_add_u32_e32 v246, 0x1c000, v232
	buffer_load_dwordx4 v0, s[24:27], s17 offen lds
	s_mov_b32 m0, s31
	s_lshl_b32 s58, s30, 8
	v_readfirstlane_b32 s31, v246
	v_add_u32_e32 v247, 0x1e000, v232
	buffer_load_dwordx4 v0, s[24:27], s2 offen lds
	s_or_b32 s2, s58, 0x80
	s_mov_b32 m0, s31
	v_readfirstlane_b32 s31, v247
	buffer_load_dwordx4 v0, s[44:47], s2 offen lds
	s_add_i32 s2, s2, s8
	s_mov_b32 m0, s31
	v_mov_b32_e32 v5, 0
	buffer_load_dwordx4 v0, s[44:47], s2 offen lds
	s_waitcnt vmcnt(6)
	s_cmpk_lt_i32 s30, 0xc0
	v_add_u32_e32 v241, 0xc000, v232
	v_add_u32_e32 v240, 0xe000, v232
	v_mov_b32_e32 v4, v5
	v_mov_b32_e32 v3, v5
	v_mov_b32_e32 v2, v5
	v_mov_b32_e32 v9, v5
	v_mov_b32_e32 v8, v5
	v_mov_b32_e32 v7, v5
	v_mov_b32_e32 v6, v5
	v_mov_b32_e32 v13, v5
	v_mov_b32_e32 v12, v5
	v_mov_b32_e32 v11, v5
	v_mov_b32_e32 v10, v5
	v_mov_b32_e32 v17, v5
	v_mov_b32_e32 v16, v5
	v_mov_b32_e32 v15, v5
	v_mov_b32_e32 v14, v5
	s_waitcnt vmcnt(13)
	v_mov_b32_e32 v21, v5
	v_mov_b32_e32 v20, v5
	v_mov_b32_e32 v19, v5
	v_mov_b32_e32 v18, v5
	s_waitcnt vmcnt(12)
	v_mov_b32_e32 v25, v5
	v_mov_b32_e32 v24, v5
	v_mov_b32_e32 v23, v5
	v_mov_b32_e32 v22, v5
	s_waitcnt vmcnt(11)
	v_mov_b32_e32 v29, v5
	v_mov_b32_e32 v28, v5
	v_mov_b32_e32 v27, v5
	v_mov_b32_e32 v26, v5
	s_waitcnt vmcnt(10)
	v_mov_b32_e32 v33, v5
	v_mov_b32_e32 v32, v5
	v_mov_b32_e32 v31, v5
	v_mov_b32_e32 v30, v5
	v_mov_b32_e32 v37, v5
	v_mov_b32_e32 v36, v5
	v_mov_b32_e32 v35, v5
	v_mov_b32_e32 v34, v5
	v_mov_b32_e32 v41, v5
	v_mov_b32_e32 v40, v5
	v_mov_b32_e32 v39, v5
	v_mov_b32_e32 v38, v5
	v_mov_b32_e32 v45, v5
	v_mov_b32_e32 v44, v5
	v_mov_b32_e32 v43, v5
	v_mov_b32_e32 v42, v5
	v_mov_b32_e32 v49, v5
	v_mov_b32_e32 v48, v5
	v_mov_b32_e32 v47, v5
	v_mov_b32_e32 v46, v5
	v_mov_b32_e32 v53, v5
	v_mov_b32_e32 v52, v5
	v_mov_b32_e32 v51, v5
	v_mov_b32_e32 v50, v5
	v_mov_b32_e32 v57, v5
	v_mov_b32_e32 v56, v5
	v_mov_b32_e32 v55, v5
	v_mov_b32_e32 v54, v5
	v_mov_b32_e32 v61, v5
	v_mov_b32_e32 v60, v5
	v_mov_b32_e32 v59, v5
	v_mov_b32_e32 v58, v5
	v_mov_b32_e32 v65, v5
	v_mov_b32_e32 v64, v5
	v_mov_b32_e32 v63, v5
	v_mov_b32_e32 v62, v5
	v_mov_b32_e32 v129, v5
	v_mov_b32_e32 v128, v5
	v_mov_b32_e32 v127, v5
	v_mov_b32_e32 v126, v5
	v_mov_b32_e32 v125, v5
	v_mov_b32_e32 v124, v5
	v_mov_b32_e32 v123, v5
	v_mov_b32_e32 v122, v5
	v_mov_b32_e32 v121, v5
	v_mov_b32_e32 v120, v5
	v_mov_b32_e32 v119, v5
	v_mov_b32_e32 v118, v5
	v_mov_b32_e32 v117, v5
	v_mov_b32_e32 v116, v5
	v_mov_b32_e32 v115, v5
	v_mov_b32_e32 v114, v5
	v_mov_b32_e32 v113, v5
	v_mov_b32_e32 v112, v5
	v_mov_b32_e32 v111, v5
	v_mov_b32_e32 v110, v5
	v_mov_b32_e32 v109, v5
	v_mov_b32_e32 v108, v5
	v_mov_b32_e32 v107, v5
	v_mov_b32_e32 v106, v5
	v_mov_b32_e32 v105, v5
	v_mov_b32_e32 v104, v5
	v_mov_b32_e32 v103, v5
	v_mov_b32_e32 v102, v5
	v_mov_b32_e32 v101, v5
	v_mov_b32_e32 v100, v5
	v_mov_b32_e32 v99, v5
	v_mov_b32_e32 v98, v5
	v_mov_b32_e32 v97, v5
	v_mov_b32_e32 v96, v5
	v_mov_b32_e32 v95, v5
	v_mov_b32_e32 v94, v5
	v_mov_b32_e32 v93, v5
	v_mov_b32_e32 v92, v5
	v_mov_b32_e32 v91, v5
	v_mov_b32_e32 v90, v5
	v_mov_b32_e32 v89, v5
	v_mov_b32_e32 v88, v5
	v_mov_b32_e32 v87, v5
	v_mov_b32_e32 v86, v5
	v_mov_b32_e32 v85, v5
	v_mov_b32_e32 v84, v5
	v_mov_b32_e32 v83, v5
	v_mov_b32_e32 v82, v5
	v_mov_b32_e32 v81, v5
	v_mov_b32_e32 v80, v5
	v_mov_b32_e32 v79, v5
	v_mov_b32_e32 v78, v5
	v_mov_b32_e32 v77, v5
	v_mov_b32_e32 v76, v5
	v_mov_b32_e32 v75, v5
	v_mov_b32_e32 v74, v5
	v_mov_b32_e32 v73, v5
	v_mov_b32_e32 v72, v5
	v_mov_b32_e32 v71, v5
	v_mov_b32_e32 v70, v5
	v_mov_b32_e32 v69, v5
	v_mov_b32_e32 v68, v5
	v_mov_b32_e32 v67, v5
	v_mov_b32_e32 v66, v5
	s_barrier
	s_cbranch_scc1 .LBB0_262
	v_lshlrev_b32_e32 v2, 6, v130
	s_add_i32 s59, s33, -2
	v_add3_u32 v2, v131, s60, v2
	s_cmp_eq_u32 s97, 1
	v_mad_i64_i32 v[2:3], s[46:47], v2, s62, 0
	s_cselect_b64 s[30:31], -1, 0
	v_lshrrev_b32_e32 v5, 1, v204
	s_lshl_b64 s[46:47], s[94:95], 1
	v_and_b32_e32 v4, 0xc0, v204
	v_and_b32_e32 v5, 24, v5
	s_add_u32 s46, s15, s46
	v_or3_b32 v2, v2, v4, v5
	s_addc_u32 s47, s16, s47
	v_mov_b32_e32 v66, 0
	v_lshl_add_u64 v[130:131], s[46:47], 0, v[2:3]
	s_mov_b32 s2, 0
	s_movk_i32 s70, 0x100
	v_mov_b32_e32 v67, v66
	v_mov_b32_e32 v68, v66
	v_mov_b32_e32 v69, v66
	v_mov_b32_e32 v70, v66
	v_mov_b32_e32 v71, v66
	v_mov_b32_e32 v72, v66
	v_mov_b32_e32 v73, v66
	v_mov_b32_e32 v74, v66
	v_mov_b32_e32 v75, v66
	v_mov_b32_e32 v76, v66
	v_mov_b32_e32 v77, v66
	v_mov_b32_e32 v78, v66
	v_mov_b32_e32 v79, v66
	v_mov_b32_e32 v80, v66
	v_mov_b32_e32 v81, v66
	v_mov_b32_e32 v82, v66
	v_mov_b32_e32 v83, v66
	v_mov_b32_e32 v84, v66
	v_mov_b32_e32 v85, v66
	v_mov_b32_e32 v86, v66
	v_mov_b32_e32 v87, v66
	v_mov_b32_e32 v88, v66
	v_mov_b32_e32 v89, v66
	v_mov_b32_e32 v90, v66
	v_mov_b32_e32 v91, v66
	v_mov_b32_e32 v92, v66
	v_mov_b32_e32 v93, v66
	v_mov_b32_e32 v94, v66
	v_mov_b32_e32 v95, v66
	v_mov_b32_e32 v96, v66
	v_mov_b32_e32 v97, v66
	v_mov_b32_e32 v98, v66
	v_mov_b32_e32 v99, v66
	v_mov_b32_e32 v100, v66
	v_mov_b32_e32 v101, v66
	v_mov_b32_e32 v102, v66
	v_mov_b32_e32 v103, v66
	v_mov_b32_e32 v104, v66
	v_mov_b32_e32 v105, v66
	v_mov_b32_e32 v106, v66
	v_mov_b32_e32 v107, v66
	v_mov_b32_e32 v108, v66
	v_mov_b32_e32 v109, v66
	v_mov_b32_e32 v110, v66
	v_mov_b32_e32 v111, v66
	v_mov_b32_e32 v112, v66
	v_mov_b32_e32 v113, v66
	v_mov_b32_e32 v114, v66
	v_mov_b32_e32 v115, v66
	v_mov_b32_e32 v116, v66
	v_mov_b32_e32 v117, v66
	v_mov_b32_e32 v118, v66
	v_mov_b32_e32 v119, v66
	v_mov_b32_e32 v120, v66
	v_mov_b32_e32 v121, v66
	v_mov_b32_e32 v122, v66
	v_mov_b32_e32 v123, v66
	v_mov_b32_e32 v124, v66
	v_mov_b32_e32 v125, v66
	v_mov_b32_e32 v126, v66
	v_mov_b32_e32 v127, v66
	v_mov_b32_e32 v128, v66
	v_mov_b32_e32 v129, v66
	v_mov_b32_e32 v62, v66
	v_mov_b32_e32 v63, v66
	v_mov_b32_e32 v64, v66
	v_mov_b32_e32 v65, v66
	v_mov_b32_e32 v58, v66
	v_mov_b32_e32 v59, v66
	v_mov_b32_e32 v60, v66
	v_mov_b32_e32 v61, v66
	v_mov_b32_e32 v54, v66
	v_mov_b32_e32 v55, v66
	v_mov_b32_e32 v56, v66
	v_mov_b32_e32 v57, v66
	v_mov_b32_e32 v50, v66
	v_mov_b32_e32 v51, v66
	v_mov_b32_e32 v52, v66
	v_mov_b32_e32 v53, v66
	v_mov_b32_e32 v46, v66
	v_mov_b32_e32 v47, v66
	v_mov_b32_e32 v48, v66
	v_mov_b32_e32 v49, v66
	v_mov_b32_e32 v42, v66
	v_mov_b32_e32 v43, v66
	v_mov_b32_e32 v44, v66
	v_mov_b32_e32 v45, v66
	v_mov_b32_e32 v38, v66
	v_mov_b32_e32 v39, v66
	v_mov_b32_e32 v40, v66
	v_mov_b32_e32 v41, v66
	v_mov_b32_e32 v34, v66
	v_mov_b32_e32 v35, v66
	v_mov_b32_e32 v36, v66
	v_mov_b32_e32 v37, v66
	v_mov_b32_e32 v30, v66
	v_mov_b32_e32 v31, v66
	v_mov_b32_e32 v32, v66
	v_mov_b32_e32 v33, v66
	v_mov_b32_e32 v26, v66
	v_mov_b32_e32 v27, v66
	v_mov_b32_e32 v28, v66
	v_mov_b32_e32 v29, v66
	v_mov_b32_e32 v22, v66
	v_mov_b32_e32 v23, v66
	v_mov_b32_e32 v24, v66
	v_mov_b32_e32 v25, v66
	v_mov_b32_e32 v18, v66
	v_mov_b32_e32 v19, v66
	v_mov_b32_e32 v20, v66
	v_mov_b32_e32 v21, v66
	v_mov_b32_e32 v14, v66
	v_mov_b32_e32 v15, v66
	v_mov_b32_e32 v16, v66
	v_mov_b32_e32 v17, v66
	v_mov_b32_e32 v10, v66
	v_mov_b32_e32 v11, v66
	v_mov_b32_e32 v12, v66
	v_mov_b32_e32 v13, v66
	v_mov_b32_e32 v6, v66
	v_mov_b32_e32 v7, v66
	v_mov_b32_e32 v8, v66
	v_mov_b32_e32 v9, v66
	v_mov_b32_e32 v2, v66
	v_mov_b32_e32 v3, v66
	v_mov_b32_e32 v4, v66
	v_mov_b32_e32 v5, v66
	v_readfirstlane_b32 s46, v204
	s_nop 3
	s_lshr_b32 s46, s46, 8
	s_cmp_eq_u32 s46, 1
	s_cbranch_scc0 .Lgprio_done
	s_setprio 1
.Lgprio_done:
	s_branch .LBB0_255
.LBB0_254:
	v_add_u32_e32 v188, v239, v238
	ds_read_b128 v[132:135], v188
	ds_read_b128 v[136:139], v188 offset:1024
	ds_read_b128 v[140:143], v188 offset:2048
	ds_read_b128 v[144:147], v188 offset:3072
	s_add_i32 s71, s58, s70
	v_readfirstlane_b32 s47, v241
	s_add_i32 s46, s71, 0xffffff80
	s_mov_b32 m0, s47
	s_add_i32 vcc_lo, s85, s70
	v_readfirstlane_b32 s47, v240
	ds_read_b128 v[148:151], v237
	ds_read_b128 v[152:155], v237 offset:1024
	ds_read_b128 v[156:159], v237 offset:2048
	ds_read_b128 v[160:163], v237 offset:3072
	ds_read_b128 v[164:167], v237 offset:4096
	ds_read_b128 v[168:171], v237 offset:5120
	ds_read_b128 v[172:175], v237 offset:6144
	ds_read_b128 v[176:179], v237 offset:7168
	buffer_load_dwordx4 v0, s[24:27], s46 offen lds
	s_add_i32 s46, vcc_lo, 0xffffff80
	s_mov_b32 m0, s47
	s_nop 0
	buffer_load_dwordx4 v0, s[24:27], s46 offen lds
	s_waitcnt lgkmcnt(8)
	s_barrier
	s_waitcnt lgkmcnt(0)
	s_waitcnt lgkmcnt(7)
	v_mfma_f32_16x16x32_bf16 v[126:129], v[132:135], v[148:151], v[126:129]
	v_mfma_f32_16x16x32_bf16 v[122:125], v[140:143], v[148:151], v[122:125]
	s_waitcnt lgkmcnt(5)
	v_mfma_f32_16x16x32_bf16 v[118:121], v[132:135], v[156:159], v[118:121]
	v_mfma_f32_16x16x32_bf16 v[114:117], v[140:143], v[156:159], v[114:117]
	s_waitcnt lgkmcnt(3)
	v_mfma_f32_16x16x32_bf16 v[110:113], v[132:135], v[164:167], v[110:113]
	v_mfma_f32_16x16x32_bf16 v[106:109], v[140:143], v[164:167], v[106:109]
	s_waitcnt lgkmcnt(1)
	v_mfma_f32_16x16x32_bf16 v[102:105], v[132:135], v[172:175], v[102:105]
	v_mfma_f32_16x16x32_bf16 v[98:101], v[140:143], v[172:175], v[98:101]
	v_mfma_f32_16x16x32_bf16 v[126:129], v[136:139], v[152:155], v[126:129]
	v_mfma_f32_16x16x32_bf16 v[122:125], v[144:147], v[152:155], v[122:125]
	v_mfma_f32_16x16x32_bf16 v[118:121], v[136:139], v[160:163], v[118:121]
	v_mfma_f32_16x16x32_bf16 v[114:117], v[144:147], v[160:163], v[114:117]
	v_mfma_f32_16x16x32_bf16 v[110:113], v[136:139], v[168:171], v[110:113]
	v_mfma_f32_16x16x32_bf16 v[106:109], v[144:147], v[168:171], v[106:109]
	s_waitcnt lgkmcnt(0)
	v_mfma_f32_16x16x32_bf16 v[102:105], v[136:139], v[176:179], v[102:105]
	v_mfma_f32_16x16x32_bf16 v[98:101], v[144:147], v[176:179], v[98:101]
	s_barrier
	v_readfirstlane_b32 s50, v236
	s_mov_b32 s46, s26
	s_mov_b32 s47, s27
	s_mov_b32 m0, s50
	v_readfirstlane_b32 s55, v235
	ds_read_b128 v[180:183], v188 offset:16384
	ds_read_b128 v[184:187], v188 offset:17408
	ds_read_b128 v[198:201], v188 offset:18432
	ds_read_b128 v[248:251], v188 offset:19456
	buffer_load_dwordx4 v0, s[44:47], s70 offen lds
	s_add_i32 s50, s8, s70
	s_mov_b32 m0, s55
	s_add_i32 s2, s2, 2
	buffer_load_dwordx4 v0, s[44:47], s50 offen lds
	s_barrier
	s_waitcnt lgkmcnt(0)
	s_waitcnt lgkmcnt(3)
	v_mfma_f32_16x16x32_bf16 v[94:97], v[180:183], v[148:151], v[94:97]
	s_waitcnt lgkmcnt(1)
	v_mfma_f32_16x16x32_bf16 v[90:93], v[198:201], v[148:151], v[90:93]
	v_mfma_f32_16x16x32_bf16 v[86:89], v[180:183], v[156:159], v[86:89]
	v_mfma_f32_16x16x32_bf16 v[82:85], v[198:201], v[156:159], v[82:85]
	v_mfma_f32_16x16x32_bf16 v[78:81], v[180:183], v[164:167], v[78:81]
	v_mfma_f32_16x16x32_bf16 v[74:77], v[198:201], v[164:167], v[74:77]
	v_mfma_f32_16x16x32_bf16 v[70:73], v[180:183], v[172:175], v[70:73]
	v_mfma_f32_16x16x32_bf16 v[66:69], v[198:201], v[172:175], v[66:69]
	v_mfma_f32_16x16x32_bf16 v[94:97], v[184:187], v[152:155], v[94:97]
	s_waitcnt lgkmcnt(0)
	v_mfma_f32_16x16x32_bf16 v[90:93], v[248:251], v[152:155], v[90:93]
	v_mfma_f32_16x16x32_bf16 v[86:89], v[184:187], v[160:163], v[86:89]
	v_mfma_f32_16x16x32_bf16 v[82:85], v[248:251], v[160:163], v[82:85]
	v_mfma_f32_16x16x32_bf16 v[78:81], v[184:187], v[168:171], v[78:81]
	v_mfma_f32_16x16x32_bf16 v[74:77], v[248:251], v[168:171], v[74:77]
	v_mfma_f32_16x16x32_bf16 v[70:73], v[184:187], v[176:179], v[70:73]
	v_mfma_f32_16x16x32_bf16 v[66:69], v[248:251], v[176:179], v[66:69]
	v_readfirstlane_b32 s55, v232
	s_mov_b32 m0, s55
	v_readfirstlane_b32 s55, v234
	s_barrier
	ds_read_b128 v[148:151], v237 offset:16384
	ds_read_b128 v[152:155], v237 offset:17408
	ds_read_b128 v[156:159], v237 offset:18432
	ds_read_b128 v[160:163], v237 offset:19456
	ds_read_b128 v[164:167], v237 offset:20480
	ds_read_b128 v[168:171], v237 offset:21504
	ds_read_b128 v[172:175], v237 offset:22528
	ds_read_b128 v[176:179], v237 offset:23552
	buffer_load_dwordx4 v0, s[24:27], s70 offen lds
	s_mov_b32 m0, s55
	s_nop 0
	buffer_load_dwordx4 v0, s[24:27], s50 offen lds
	s_barrier
	s_waitcnt lgkmcnt(0)
	s_waitcnt lgkmcnt(7)
	v_mfma_f32_16x16x32_bf16 v[62:65], v[132:135], v[148:151], v[62:65]
	v_mfma_f32_16x16x32_bf16 v[58:61], v[140:143], v[148:151], v[58:61]
	s_waitcnt lgkmcnt(5)
	v_mfma_f32_16x16x32_bf16 v[54:57], v[132:135], v[156:159], v[54:57]
	v_mfma_f32_16x16x32_bf16 v[50:53], v[140:143], v[156:159], v[50:53]
	s_waitcnt lgkmcnt(3)
	v_mfma_f32_16x16x32_bf16 v[46:49], v[132:135], v[164:167], v[46:49]
	v_mfma_f32_16x16x32_bf16 v[42:45], v[140:143], v[164:167], v[42:45]
	s_waitcnt lgkmcnt(1)
	v_mfma_f32_16x16x32_bf16 v[38:41], v[132:135], v[172:175], v[38:41]
	v_mfma_f32_16x16x32_bf16 v[34:37], v[140:143], v[172:175], v[34:37]
	v_mfma_f32_16x16x32_bf16 v[62:65], v[136:139], v[152:155], v[62:65]
	v_mfma_f32_16x16x32_bf16 v[58:61], v[144:147], v[152:155], v[58:61]
	v_mfma_f32_16x16x32_bf16 v[54:57], v[136:139], v[160:163], v[54:57]
	v_mfma_f32_16x16x32_bf16 v[50:53], v[144:147], v[160:163], v[50:53]
	v_mfma_f32_16x16x32_bf16 v[46:49], v[136:139], v[168:171], v[46:49]
	v_mfma_f32_16x16x32_bf16 v[42:45], v[144:147], v[168:171], v[42:45]
	s_waitcnt lgkmcnt(0)
	v_mfma_f32_16x16x32_bf16 v[38:41], v[136:139], v[176:179], v[38:41]
	v_mfma_f32_16x16x32_bf16 v[34:37], v[144:147], v[176:179], v[34:37]
	s_barrier
	v_readfirstlane_b32 s55, v233
	s_mov_b32 m0, s55
	v_readfirstlane_b32 s55, v231
	buffer_load_dwordx4 v0, s[44:47], s71 offen lds
	s_mov_b32 m0, s55
	s_nop 0
	buffer_load_dwordx4 v0, s[44:47], vcc_lo offen lds
	s_waitcnt vmcnt(6)
	s_barrier
	v_mfma_f32_16x16x32_bf16 v[30:33], v[180:183], v[148:151], v[30:33]
	v_mfma_f32_16x16x32_bf16 v[26:29], v[198:201], v[148:151], v[26:29]
	v_mfma_f32_16x16x32_bf16 v[22:25], v[180:183], v[156:159], v[22:25]
	v_mfma_f32_16x16x32_bf16 v[18:21], v[198:201], v[156:159], v[18:21]
	v_mfma_f32_16x16x32_bf16 v[14:17], v[180:183], v[164:167], v[14:17]
	v_mfma_f32_16x16x32_bf16 v[10:13], v[198:201], v[164:167], v[10:13]
	v_mfma_f32_16x16x32_bf16 v[6:9], v[180:183], v[172:175], v[6:9]
	v_mfma_f32_16x16x32_bf16 v[2:5], v[198:201], v[172:175], v[2:5]
	v_mfma_f32_16x16x32_bf16 v[30:33], v[184:187], v[152:155], v[30:33]
	v_mfma_f32_16x16x32_bf16 v[26:29], v[248:251], v[152:155], v[26:29]
	v_mfma_f32_16x16x32_bf16 v[22:25], v[184:187], v[160:163], v[22:25]
	v_mfma_f32_16x16x32_bf16 v[18:21], v[248:251], v[160:163], v[18:21]
	v_mfma_f32_16x16x32_bf16 v[14:17], v[184:187], v[168:171], v[14:17]
	v_mfma_f32_16x16x32_bf16 v[10:13], v[248:251], v[168:171], v[10:13]
	v_mfma_f32_16x16x32_bf16 v[6:9], v[184:187], v[176:179], v[6:9]
	v_mfma_f32_16x16x32_bf16 v[2:5], v[248:251], v[176:179], v[2:5]
	s_barrier
	ds_read_b128 v[132:135], v188 offset:32768
	ds_read_b128 v[136:139], v188 offset:33792
	ds_read_b128 v[140:143], v188 offset:34816
	ds_read_b128 v[144:147], v188 offset:35840
	v_readfirstlane_b32 s55, v230
	s_mov_b32 m0, s55
	v_readfirstlane_b32 s55, v205
	ds_read_b128 v[148:151], v237 offset:32768
	ds_read_b128 v[152:155], v237 offset:33792
	ds_read_b128 v[156:159], v237 offset:34816
	ds_read_b128 v[160:163], v237 offset:35840
	ds_read_b128 v[164:167], v237 offset:36864
	ds_read_b128 v[168:171], v237 offset:37888
	ds_read_b128 v[172:175], v237 offset:38912
	ds_read_b128 v[176:179], v237 offset:39936
	buffer_load_dwordx4 v0, s[24:27], s71 offen lds
	s_mov_b32 m0, s55
	s_nop 0
	buffer_load_dwordx4 v0, s[24:27], vcc_lo offen lds
	s_waitcnt lgkmcnt(8)
	s_barrier
	s_waitcnt lgkmcnt(0)
	s_waitcnt lgkmcnt(7)
	v_mfma_f32_16x16x32_bf16 v[126:129], v[132:135], v[148:151], v[126:129]
	v_mfma_f32_16x16x32_bf16 v[122:125], v[140:143], v[148:151], v[122:125]
	s_waitcnt lgkmcnt(5)
	v_mfma_f32_16x16x32_bf16 v[118:121], v[132:135], v[156:159], v[118:121]
	v_mfma_f32_16x16x32_bf16 v[114:117], v[140:143], v[156:159], v[114:117]
	s_waitcnt lgkmcnt(3)
	v_mfma_f32_16x16x32_bf16 v[110:113], v[132:135], v[164:167], v[110:113]
	v_mfma_f32_16x16x32_bf16 v[106:109], v[140:143], v[164:167], v[106:109]
	s_waitcnt lgkmcnt(1)
	v_mfma_f32_16x16x32_bf16 v[102:105], v[132:135], v[172:175], v[102:105]
	v_mfma_f32_16x16x32_bf16 v[98:101], v[140:143], v[172:175], v[98:101]
	v_mfma_f32_16x16x32_bf16 v[126:129], v[136:139], v[152:155], v[126:129]
	v_mfma_f32_16x16x32_bf16 v[122:125], v[144:147], v[152:155], v[122:125]
	v_mfma_f32_16x16x32_bf16 v[118:121], v[136:139], v[160:163], v[118:121]
	v_mfma_f32_16x16x32_bf16 v[114:117], v[144:147], v[160:163], v[114:117]
	v_mfma_f32_16x16x32_bf16 v[110:113], v[136:139], v[168:171], v[110:113]
	v_mfma_f32_16x16x32_bf16 v[106:109], v[144:147], v[168:171], v[106:109]
	s_waitcnt lgkmcnt(0)
	v_mfma_f32_16x16x32_bf16 v[102:105], v[136:139], v[176:179], v[102:105]
	v_mfma_f32_16x16x32_bf16 v[98:101], v[144:147], v[176:179], v[98:101]
	s_barrier
	v_readfirstlane_b32 s87, v242
	s_add_i32 s55, s70, 0x80
	s_mov_b32 m0, s87
	v_readfirstlane_b32 s87, v243
	ds_read_b128 v[180:183], v188 offset:49152
	ds_read_b128 v[184:187], v188 offset:50176
	ds_read_b128 v[198:201], v188 offset:51200
	ds_read_b128 v[248:251], v188 offset:52224
	buffer_load_dwordx4 v0, s[44:47], s55 offen lds
	s_addk_i32 s50, 0x80
	s_mov_b32 m0, s87
	s_nop 0
	buffer_load_dwordx4 v0, s[44:47], s50 offen lds
	s_barrier
	s_waitcnt lgkmcnt(0)
	s_waitcnt lgkmcnt(3)
	v_mfma_f32_16x16x32_bf16 v[94:97], v[180:183], v[148:151], v[94:97]
	s_waitcnt lgkmcnt(1)
	v_mfma_f32_16x16x32_bf16 v[90:93], v[198:201], v[148:151], v[90:93]
	v_mfma_f32_16x16x32_bf16 v[86:89], v[180:183], v[156:159], v[86:89]
	v_mfma_f32_16x16x32_bf16 v[82:85], v[198:201], v[156:159], v[82:85]
	v_mfma_f32_16x16x32_bf16 v[78:81], v[180:183], v[164:167], v[78:81]
	v_mfma_f32_16x16x32_bf16 v[74:77], v[198:201], v[164:167], v[74:77]
	v_mfma_f32_16x16x32_bf16 v[70:73], v[180:183], v[172:175], v[70:73]
	v_mfma_f32_16x16x32_bf16 v[66:69], v[198:201], v[172:175], v[66:69]
	v_mfma_f32_16x16x32_bf16 v[94:97], v[184:187], v[152:155], v[94:97]
	s_waitcnt lgkmcnt(0)
	v_mfma_f32_16x16x32_bf16 v[90:93], v[248:251], v[152:155], v[90:93]
	v_mfma_f32_16x16x32_bf16 v[86:89], v[184:187], v[160:163], v[86:89]
	v_mfma_f32_16x16x32_bf16 v[82:85], v[248:251], v[160:163], v[82:85]
	v_mfma_f32_16x16x32_bf16 v[78:81], v[184:187], v[168:171], v[78:81]
	v_mfma_f32_16x16x32_bf16 v[74:77], v[248:251], v[168:171], v[74:77]
	v_mfma_f32_16x16x32_bf16 v[70:73], v[184:187], v[176:179], v[70:73]
	v_mfma_f32_16x16x32_bf16 v[66:69], v[248:251], v[176:179], v[66:69]
	v_readfirstlane_b32 s87, v244
	s_mov_b32 m0, s87
	s_barrier
	ds_read_b128 v[148:151], v237 offset:49152
	ds_read_b128 v[152:155], v237 offset:50176
	ds_read_b128 v[156:159], v237 offset:51200
	ds_read_b128 v[160:163], v237 offset:52224
	ds_read_b128 v[164:167], v237 offset:53248
	ds_read_b128 v[168:171], v237 offset:54272
	ds_read_b128 v[172:175], v237 offset:55296
	ds_read_b128 v[176:179], v237 offset:56320
	buffer_load_dwordx4 v0, s[24:27], s55 offen lds
	v_readfirstlane_b32 s55, v245
	s_mov_b32 m0, s55
	s_nop 0
	buffer_load_dwordx4 v0, s[24:27], s50 offen lds
	s_barrier
	s_waitcnt lgkmcnt(0)
	s_waitcnt lgkmcnt(7)
	v_mfma_f32_16x16x32_bf16 v[62:65], v[132:135], v[148:151], v[62:65]
	v_mfma_f32_16x16x32_bf16 v[58:61], v[140:143], v[148:151], v[58:61]
	s_waitcnt lgkmcnt(5)
	v_mfma_f32_16x16x32_bf16 v[54:57], v[132:135], v[156:159], v[54:57]
	v_mfma_f32_16x16x32_bf16 v[50:53], v[140:143], v[156:159], v[50:53]
	s_waitcnt lgkmcnt(3)
	v_mfma_f32_16x16x32_bf16 v[46:49], v[132:135], v[164:167], v[46:49]
	v_mfma_f32_16x16x32_bf16 v[42:45], v[140:143], v[164:167], v[42:45]
	s_waitcnt lgkmcnt(1)
	v_mfma_f32_16x16x32_bf16 v[38:41], v[132:135], v[172:175], v[38:41]
	v_mfma_f32_16x16x32_bf16 v[34:37], v[140:143], v[172:175], v[34:37]
	v_mfma_f32_16x16x32_bf16 v[62:65], v[136:139], v[152:155], v[62:65]
	v_mfma_f32_16x16x32_bf16 v[58:61], v[144:147], v[152:155], v[58:61]
	v_mfma_f32_16x16x32_bf16 v[54:57], v[136:139], v[160:163], v[54:57]
	v_mfma_f32_16x16x32_bf16 v[50:53], v[144:147], v[160:163], v[50:53]
	v_mfma_f32_16x16x32_bf16 v[46:49], v[136:139], v[168:171], v[46:49]
	v_mfma_f32_16x16x32_bf16 v[42:45], v[144:147], v[168:171], v[42:45]
	s_waitcnt lgkmcnt(0)
	v_mfma_f32_16x16x32_bf16 v[38:41], v[136:139], v[176:179], v[38:41]
	v_mfma_f32_16x16x32_bf16 v[34:37], v[144:147], v[176:179], v[34:37]
	s_barrier
	v_readfirstlane_b32 s50, v246
	s_addk_i32 s71, 0x80
	s_mov_b32 m0, s50
	v_readfirstlane_b32 s50, v247
	buffer_load_dwordx4 v0, s[44:47], s71 offen lds
	s_addk_i32 vcc_lo, 0x80
	s_mov_b32 m0, s50
	s_nop 0
	buffer_load_dwordx4 v0, s[44:47], vcc_lo offen lds
	s_waitcnt vmcnt(6)
	s_barrier
	v_mfma_f32_16x16x32_bf16 v[30:33], v[180:183], v[148:151], v[30:33]
	v_mfma_f32_16x16x32_bf16 v[26:29], v[198:201], v[148:151], v[26:29]
	v_mfma_f32_16x16x32_bf16 v[22:25], v[180:183], v[156:159], v[22:25]
	v_mfma_f32_16x16x32_bf16 v[18:21], v[198:201], v[156:159], v[18:21]
	v_mfma_f32_16x16x32_bf16 v[14:17], v[180:183], v[164:167], v[14:17]
	v_mfma_f32_16x16x32_bf16 v[10:13], v[198:201], v[164:167], v[10:13]
	v_mfma_f32_16x16x32_bf16 v[6:9], v[180:183], v[172:175], v[6:9]
	v_mfma_f32_16x16x32_bf16 v[2:5], v[198:201], v[172:175], v[2:5]
	v_mfma_f32_16x16x32_bf16 v[30:33], v[184:187], v[152:155], v[30:33]
	v_mfma_f32_16x16x32_bf16 v[26:29], v[248:251], v[152:155], v[26:29]
	v_mfma_f32_16x16x32_bf16 v[22:25], v[184:187], v[160:163], v[22:25]
	v_mfma_f32_16x16x32_bf16 v[18:21], v[248:251], v[160:163], v[18:21]
	v_mfma_f32_16x16x32_bf16 v[14:17], v[184:187], v[168:171], v[14:17]
	v_mfma_f32_16x16x32_bf16 v[10:13], v[248:251], v[168:171], v[10:13]
	v_mfma_f32_16x16x32_bf16 v[6:9], v[184:187], v[176:179], v[6:9]
	v_mfma_f32_16x16x32_bf16 v[2:5], v[248:251], v[176:179], v[2:5]
	s_addk_i32 s70, 0x100
	s_mov_b64 s[46:47], 0x200
	s_cmp_ge_i32 s2, s59
	v_lshl_add_u64 v[130:131], v[130:131], 0, s[46:47]
	s_barrier
	s_cbranch_scc1 .LBB0_262

.LBB0_262:
	s_and_b64 s[6:7], exec, s[6:7]
	s_or_b64 s[92:93], s[6:7], s[92:93]
	s_lshl_b32 s2, s33, 7
	s_add_i32 s2, s58, s2
	v_readfirstlane_b32 s6, v241
	v_add_u32_e32 v202, v239, v238
	s_addk_i32 s2, 0xff80
	s_mov_b32 m0, s6
	v_readfirstlane_b32 s6, v240
	ds_read_b128 v[130:133], v202
	ds_read_b128 v[134:137], v202 offset:1024
	ds_read_b128 v[138:141], v202 offset:2048
	ds_read_b128 v[142:145], v202 offset:3072
	ds_read_b128 v[146:149], v237
	ds_read_b128 v[150:153], v237 offset:1024
	ds_read_b128 v[154:157], v237 offset:2048
	ds_read_b128 v[158:161], v237 offset:3072
	ds_read_b128 v[162:165], v237 offset:4096
	ds_read_b128 v[166:169], v237 offset:5120
	ds_read_b128 v[170:173], v237 offset:6144
	ds_read_b128 v[174:177], v237 offset:7168
	buffer_load_dwordx4 v0, s[24:27], s2 offen lds
	s_add_i32 s2, s2, s8
	s_mov_b32 m0, s6
	s_nop 0
	buffer_load_dwordx4 v0, s[24:27], s2 offen lds
	s_barrier
	s_waitcnt lgkmcnt(0)
	s_waitcnt lgkmcnt(7)
	v_mfma_f32_16x16x32_bf16 v[126:129], v[130:133], v[146:149], v[126:129]
	v_mfma_f32_16x16x32_bf16 v[122:125], v[138:141], v[146:149], v[122:125]
	s_waitcnt lgkmcnt(5)
	v_mfma_f32_16x16x32_bf16 v[118:121], v[130:133], v[154:157], v[118:121]
	v_mfma_f32_16x16x32_bf16 v[114:117], v[138:141], v[154:157], v[114:117]
	s_waitcnt lgkmcnt(3)
	v_mfma_f32_16x16x32_bf16 v[110:113], v[130:133], v[162:165], v[110:113]
	v_mfma_f32_16x16x32_bf16 v[106:109], v[138:141], v[162:165], v[106:109]
	s_waitcnt lgkmcnt(1)
	v_mfma_f32_16x16x32_bf16 v[102:105], v[130:133], v[170:173], v[102:105]
	v_mfma_f32_16x16x32_bf16 v[98:101], v[138:141], v[170:173], v[98:101]
	v_mfma_f32_16x16x32_bf16 v[126:129], v[134:137], v[150:153], v[126:129]
	v_mfma_f32_16x16x32_bf16 v[122:125], v[142:145], v[150:153], v[122:125]
	v_mfma_f32_16x16x32_bf16 v[118:121], v[134:137], v[158:161], v[118:121]
	v_mfma_f32_16x16x32_bf16 v[114:117], v[142:145], v[158:161], v[114:117]
	v_mfma_f32_16x16x32_bf16 v[110:113], v[134:137], v[166:169], v[110:113]
	v_mfma_f32_16x16x32_bf16 v[106:109], v[142:145], v[166:169], v[106:109]
	s_waitcnt lgkmcnt(0)
	v_mfma_f32_16x16x32_bf16 v[102:105], v[134:137], v[174:177], v[102:105]
	v_mfma_f32_16x16x32_bf16 v[98:101], v[142:145], v[174:177], v[98:101]
	s_barrier
	ds_read_b128 v[178:181], v202 offset:16384
	ds_read_b128 v[182:185], v202 offset:17408
	ds_read_b128 v[186:189], v202 offset:18432
	ds_read_b128 v[198:201], v202 offset:19456
	s_barrier
	s_waitcnt lgkmcnt(0)
	s_waitcnt lgkmcnt(3)
	v_mfma_f32_16x16x32_bf16 v[94:97], v[178:181], v[146:149], v[94:97]
	s_waitcnt lgkmcnt(1)
	v_mfma_f32_16x16x32_bf16 v[90:93], v[186:189], v[146:149], v[90:93]
	v_mfma_f32_16x16x32_bf16 v[86:89], v[178:181], v[154:157], v[86:89]
	v_mfma_f32_16x16x32_bf16 v[82:85], v[186:189], v[154:157], v[82:85]
	v_mfma_f32_16x16x32_bf16 v[78:81], v[178:181], v[162:165], v[78:81]
	v_mfma_f32_16x16x32_bf16 v[74:77], v[186:189], v[162:165], v[74:77]
	v_mfma_f32_16x16x32_bf16 v[70:73], v[178:181], v[170:173], v[70:73]
	v_mfma_f32_16x16x32_bf16 v[66:69], v[186:189], v[170:173], v[66:69]
	v_mfma_f32_16x16x32_bf16 v[94:97], v[182:185], v[150:153], v[94:97]
	s_waitcnt lgkmcnt(0)
	v_mfma_f32_16x16x32_bf16 v[90:93], v[198:201], v[150:153], v[90:93]
	v_mfma_f32_16x16x32_bf16 v[86:89], v[182:185], v[158:161], v[86:89]
	v_mfma_f32_16x16x32_bf16 v[82:85], v[198:201], v[158:161], v[82:85]
	v_mfma_f32_16x16x32_bf16 v[78:81], v[182:185], v[166:169], v[78:81]
	v_mfma_f32_16x16x32_bf16 v[74:77], v[198:201], v[166:169], v[74:77]
	v_mfma_f32_16x16x32_bf16 v[70:73], v[182:185], v[174:177], v[70:73]
	v_mfma_f32_16x16x32_bf16 v[66:69], v[198:201], v[174:177], v[66:69]
	s_barrier
	ds_read_b128 v[146:149], v237 offset:16384
	ds_read_b128 v[150:153], v237 offset:17408
	ds_read_b128 v[154:157], v237 offset:18432
	ds_read_b128 v[158:161], v237 offset:19456
	ds_read_b128 v[162:165], v237 offset:20480
	ds_read_b128 v[166:169], v237 offset:21504
	ds_read_b128 v[170:173], v237 offset:22528
	ds_read_b128 v[174:177], v237 offset:23552
	s_waitcnt vmcnt(4)
	s_barrier
	s_waitcnt lgkmcnt(0)
	s_waitcnt lgkmcnt(7)
	v_mfma_f32_16x16x32_bf16 v[62:65], v[130:133], v[146:149], v[62:65]
	v_mfma_f32_16x16x32_bf16 v[58:61], v[138:141], v[146:149], v[58:61]
	s_waitcnt lgkmcnt(5)
	v_mfma_f32_16x16x32_bf16 v[54:57], v[130:133], v[154:157], v[54:57]
	v_mfma_f32_16x16x32_bf16 v[50:53], v[138:141], v[154:157], v[50:53]
	s_waitcnt lgkmcnt(3)
	v_mfma_f32_16x16x32_bf16 v[46:49], v[130:133], v[162:165], v[46:49]
	v_mfma_f32_16x16x32_bf16 v[42:45], v[138:141], v[162:165], v[42:45]
	s_waitcnt lgkmcnt(1)
	v_mfma_f32_16x16x32_bf16 v[38:41], v[130:133], v[170:173], v[38:41]
	v_mfma_f32_16x16x32_bf16 v[34:37], v[138:141], v[170:173], v[34:37]
	v_mfma_f32_16x16x32_bf16 v[62:65], v[134:137], v[150:153], v[62:65]
	v_mfma_f32_16x16x32_bf16 v[58:61], v[142:145], v[150:153], v[58:61]
	v_mfma_f32_16x16x32_bf16 v[54:57], v[134:137], v[158:161], v[54:57]
	v_mfma_f32_16x16x32_bf16 v[50:53], v[142:145], v[158:161], v[50:53]
	v_mfma_f32_16x16x32_bf16 v[46:49], v[134:137], v[166:169], v[46:49]
	v_mfma_f32_16x16x32_bf16 v[42:45], v[142:145], v[166:169], v[42:45]
	s_waitcnt lgkmcnt(0)
	v_mfma_f32_16x16x32_bf16 v[38:41], v[134:137], v[174:177], v[38:41]
	v_mfma_f32_16x16x32_bf16 v[34:37], v[142:145], v[174:177], v[34:37]
	v_mfma_f32_16x16x32_bf16 v[30:33], v[178:181], v[146:149], v[30:33]
	v_mfma_f32_16x16x32_bf16 v[26:29], v[186:189], v[146:149], v[26:29]
	v_mfma_f32_16x16x32_bf16 v[22:25], v[178:181], v[154:157], v[22:25]
	v_mfma_f32_16x16x32_bf16 v[18:21], v[186:189], v[154:157], v[18:21]
	v_mfma_f32_16x16x32_bf16 v[14:17], v[178:181], v[162:165], v[14:17]
	v_mfma_f32_16x16x32_bf16 v[10:13], v[186:189], v[162:165], v[10:13]
	v_mfma_f32_16x16x32_bf16 v[6:9], v[178:181], v[170:173], v[6:9]
	v_mfma_f32_16x16x32_bf16 v[2:5], v[186:189], v[170:173], v[2:5]
	v_mfma_f32_16x16x32_bf16 v[30:33], v[182:185], v[150:153], v[30:33]
	v_mfma_f32_16x16x32_bf16 v[26:29], v[198:201], v[150:153], v[26:29]
	v_mfma_f32_16x16x32_bf16 v[22:25], v[182:185], v[158:161], v[22:25]
	v_mfma_f32_16x16x32_bf16 v[18:21], v[198:201], v[158:161], v[18:21]
	v_mfma_f32_16x16x32_bf16 v[14:17], v[182:185], v[166:169], v[14:17]
	v_mfma_f32_16x16x32_bf16 v[10:13], v[198:201], v[166:169], v[10:13]
	v_mfma_f32_16x16x32_bf16 v[6:9], v[182:185], v[174:177], v[6:9]
	v_mfma_f32_16x16x32_bf16 v[2:5], v[198:201], v[174:177], v[2:5]
	s_barrier
	ds_read_b128 v[130:133], v202 offset:32768
	ds_read_b128 v[134:137], v202 offset:33792
	ds_read_b128 v[138:141], v202 offset:34816
	ds_read_b128 v[142:145], v202 offset:35840
	ds_read_b128 v[146:149], v237 offset:32768
	ds_read_b128 v[150:153], v237 offset:33792
	ds_read_b128 v[154:157], v237 offset:34816
	ds_read_b128 v[158:161], v237 offset:35840
	ds_read_b128 v[162:165], v237 offset:36864
	ds_read_b128 v[166:169], v237 offset:37888
	ds_read_b128 v[170:173], v237 offset:38912
	ds_read_b128 v[174:177], v237 offset:39936
	s_waitcnt vmcnt(2)
	s_barrier
	s_waitcnt lgkmcnt(0)
	s_waitcnt lgkmcnt(7)
	v_mfma_f32_16x16x32_bf16 v[126:129], v[130:133], v[146:149], v[126:129]
	v_mfma_f32_16x16x32_bf16 v[122:125], v[138:141], v[146:149], v[122:125]
	s_waitcnt lgkmcnt(5)
	v_mfma_f32_16x16x32_bf16 v[118:121], v[130:133], v[154:157], v[118:121]
	v_mfma_f32_16x16x32_bf16 v[114:117], v[138:141], v[154:157], v[114:117]
	s_waitcnt lgkmcnt(3)
	v_mfma_f32_16x16x32_bf16 v[110:113], v[130:133], v[162:165], v[110:113]
	v_mfma_f32_16x16x32_bf16 v[106:109], v[138:141], v[162:165], v[106:109]
	s_waitcnt lgkmcnt(1)
	v_mfma_f32_16x16x32_bf16 v[102:105], v[130:133], v[170:173], v[102:105]
	v_mfma_f32_16x16x32_bf16 v[98:101], v[138:141], v[170:173], v[98:101]
	v_mfma_f32_16x16x32_bf16 v[126:129], v[134:137], v[150:153], v[126:129]
	v_mfma_f32_16x16x32_bf16 v[122:125], v[142:145], v[150:153], v[122:125]
	v_mfma_f32_16x16x32_bf16 v[118:121], v[134:137], v[158:161], v[118:121]
	v_mfma_f32_16x16x32_bf16 v[114:117], v[142:145], v[158:161], v[114:117]
	v_mfma_f32_16x16x32_bf16 v[110:113], v[134:137], v[166:169], v[110:113]
	v_mfma_f32_16x16x32_bf16 v[106:109], v[142:145], v[166:169], v[106:109]
	s_waitcnt lgkmcnt(0)
	v_mfma_f32_16x16x32_bf16 v[102:105], v[134:137], v[174:177], v[102:105]
	v_mfma_f32_16x16x32_bf16 v[98:101], v[142:145], v[174:177], v[98:101]
	s_barrier
	ds_read_b128 v[178:181], v202 offset:49152
	ds_read_b128 v[182:185], v202 offset:50176
	ds_read_b128 v[186:189], v202 offset:51200
	ds_read_b128 v[198:201], v202 offset:52224
	s_waitcnt vmcnt(0)
	s_barrier
	s_waitcnt lgkmcnt(0)
	s_waitcnt lgkmcnt(3)
	v_mfma_f32_16x16x32_bf16 v[94:97], v[178:181], v[146:149], v[94:97]
	s_waitcnt lgkmcnt(1)
	v_mfma_f32_16x16x32_bf16 v[90:93], v[186:189], v[146:149], v[90:93]
	v_mfma_f32_16x16x32_bf16 v[86:89], v[178:181], v[154:157], v[86:89]
	v_mfma_f32_16x16x32_bf16 v[82:85], v[186:189], v[154:157], v[82:85]
	v_mfma_f32_16x16x32_bf16 v[78:81], v[178:181], v[162:165], v[78:81]
	v_mfma_f32_16x16x32_bf16 v[74:77], v[186:189], v[162:165], v[74:77]
	v_mfma_f32_16x16x32_bf16 v[70:73], v[178:181], v[170:173], v[70:73]
	v_mfma_f32_16x16x32_bf16 v[66:69], v[186:189], v[170:173], v[66:69]
	v_mfma_f32_16x16x32_bf16 v[94:97], v[182:185], v[150:153], v[94:97]
	s_waitcnt lgkmcnt(0)
	v_mfma_f32_16x16x32_bf16 v[90:93], v[198:201], v[150:153], v[90:93]
	v_mfma_f32_16x16x32_bf16 v[86:89], v[182:185], v[158:161], v[86:89]
	v_mfma_f32_16x16x32_bf16 v[82:85], v[198:201], v[158:161], v[82:85]
	v_mfma_f32_16x16x32_bf16 v[78:81], v[182:185], v[166:169], v[78:81]
	v_mfma_f32_16x16x32_bf16 v[74:77], v[198:201], v[166:169], v[74:77]
	v_mfma_f32_16x16x32_bf16 v[70:73], v[182:185], v[174:177], v[70:73]
	v_mfma_f32_16x16x32_bf16 v[66:69], v[198:201], v[174:177], v[66:69]
	s_barrier
	ds_read_b128 v[146:149], v237 offset:49152
	ds_read_b128 v[150:153], v237 offset:50176
	ds_read_b128 v[154:157], v237 offset:51200
	ds_read_b128 v[158:161], v237 offset:52224
	ds_read_b128 v[162:165], v237 offset:53248
	ds_read_b128 v[166:169], v237 offset:54272
	ds_read_b128 v[170:173], v237 offset:55296
	ds_read_b128 v[174:177], v237 offset:56320
	s_barrier
	s_waitcnt lgkmcnt(0)
	s_waitcnt lgkmcnt(7)
	v_mfma_f32_16x16x32_bf16 v[62:65], v[130:133], v[146:149], v[62:65]
	v_mfma_f32_16x16x32_bf16 v[58:61], v[138:141], v[146:149], v[58:61]
	s_waitcnt lgkmcnt(5)
	v_mfma_f32_16x16x32_bf16 v[54:57], v[130:133], v[154:157], v[54:57]
	v_mfma_f32_16x16x32_bf16 v[50:53], v[138:141], v[154:157], v[50:53]
	s_waitcnt lgkmcnt(3)
	v_mfma_f32_16x16x32_bf16 v[46:49], v[130:133], v[162:165], v[46:49]
	v_mfma_f32_16x16x32_bf16 v[42:45], v[138:141], v[162:165], v[42:45]
	s_waitcnt lgkmcnt(1)
	v_mfma_f32_16x16x32_bf16 v[38:41], v[130:133], v[170:173], v[38:41]
	v_mfma_f32_16x16x32_bf16 v[34:37], v[138:141], v[170:173], v[34:37]
	v_mfma_f32_16x16x32_bf16 v[62:65], v[134:137], v[150:153], v[62:65]
	v_mfma_f32_16x16x32_bf16 v[58:61], v[142:145], v[150:153], v[58:61]
	v_mfma_f32_16x16x32_bf16 v[54:57], v[134:137], v[158:161], v[54:57]
	v_mfma_f32_16x16x32_bf16 v[50:53], v[142:145], v[158:161], v[50:53]
	v_mfma_f32_16x16x32_bf16 v[46:49], v[134:137], v[166:169], v[46:49]
	v_mfma_f32_16x16x32_bf16 v[42:45], v[142:145], v[166:169], v[42:45]
	s_waitcnt lgkmcnt(0)
	v_mfma_f32_16x16x32_bf16 v[38:41], v[134:137], v[174:177], v[38:41]
	v_mfma_f32_16x16x32_bf16 v[34:37], v[142:145], v[174:177], v[34:37]
	v_mfma_f32_16x16x32_bf16 v[30:33], v[178:181], v[146:149], v[30:33]
	v_mfma_f32_16x16x32_bf16 v[26:29], v[186:189], v[146:149], v[26:29]
	v_mfma_f32_16x16x32_bf16 v[22:25], v[178:181], v[154:157], v[22:25]
	v_mfma_f32_16x16x32_bf16 v[18:21], v[186:189], v[154:157], v[18:21]
	v_mfma_f32_16x16x32_bf16 v[14:17], v[178:181], v[162:165], v[14:17]
	v_mfma_f32_16x16x32_bf16 v[10:13], v[186:189], v[162:165], v[10:13]
	v_mfma_f32_16x16x32_bf16 v[6:9], v[178:181], v[170:173], v[6:9]
	v_mfma_f32_16x16x32_bf16 v[2:5], v[186:189], v[170:173], v[2:5]
	v_mfma_f32_16x16x32_bf16 v[30:33], v[182:185], v[150:153], v[30:33]
	v_mfma_f32_16x16x32_bf16 v[26:29], v[198:201], v[150:153], v[26:29]
	v_mfma_f32_16x16x32_bf16 v[22:25], v[182:185], v[158:161], v[22:25]
	v_mfma_f32_16x16x32_bf16 v[18:21], v[198:201], v[158:161], v[18:21]
	v_mfma_f32_16x16x32_bf16 v[14:17], v[182:185], v[166:169], v[14:17]
	v_mfma_f32_16x16x32_bf16 v[10:13], v[198:201], v[166:169], v[10:13]
	v_mfma_f32_16x16x32_bf16 v[6:9], v[182:185], v[174:177], v[6:9]
	v_mfma_f32_16x16x32_bf16 v[2:5], v[198:201], v[174:177], v[2:5]
	s_movk_i32 s2, 0x100
	v_cmp_gt_u32_e32 vcc, s2, v204
	s_barrier
	s_and_saveexec_b64 s[6:7], vcc
	s_cbranch_execz .LBB0_264
	s_barrier
.LBB0_264:
	s_setprio 0
	s_or_b64 exec, exec, s[6:7]
	s_andn2_b64 vcc, exec, s[28:29]
	s_cbranch_vccnz .LBB0_266
	s_ashr_i32 s2, s13, 31
	s_mul_hi_u32 s6, s74, s13
	s_mul_i32 s2, s74, s2
	s_add_i32 s2, s6, s2
	s_mul_i32 s6, s75, s13
	s_add_i32 s2, s2, s6
	s_mul_i32 s6, s74, s13
	s_add_u32 s24, s84, s6
	s_addc_u32 s2, s77, s2
	s_and_b32 s25, s2, 0xffff
	s_ashr_i32 s2, s9, 31
	s_mul_hi_u32 s6, s74, s9
	s_mul_i32 s2, s74, s2
	s_add_i32 s2, s6, s2
	s_mul_i32 s6, s75, s9
	s_add_i32 s2, s2, s6
	s_mul_i32 s6, s74, s9
	s_add_u32 s28, s76, s6
	s_addc_u32 s2, s83, s2
	s_and_b32 s29, s2, 0xffff
	v_readfirstlane_b32 s2, v236
	s_mov_b32 s30, s26
	s_mov_b32 s31, s27
	s_mov_b32 m0, s2
	v_readfirstlane_b32 s2, v235
	buffer_load_dwordx4 v0, s[28:31], 0 offen lds
	s_mov_b32 m0, s2
	v_readfirstlane_b32 s2, v232
	buffer_load_dwordx4 v0, s[28:31], s8 offen lds
	s_mov_b32 m0, s2
	v_readfirstlane_b32 s2, v234
	buffer_load_dwordx4 v0, s[24:27], 0 offen lds
	s_mov_b32 m0, s2
	v_readfirstlane_b32 s2, v233
	buffer_load_dwordx4 v0, s[24:27], s8 offen lds
	s_mov_b32 m0, s2
	v_readfirstlane_b32 s2, v231
	buffer_load_dwordx4 v0, s[28:31], s58 offen lds
	s_mov_b32 m0, s2
	v_readfirstlane_b32 s2, v230
	buffer_load_dwordx4 v0, s[28:31], s85 offen lds
	s_mov_b32 m0, s2
	v_readfirstlane_b32 s2, v205
	buffer_load_dwordx4 v0, s[24:27], s58 offen lds
	s_mov_b32 m0, s2
	s_nop 0
	buffer_load_dwordx4 v0, s[24:27], s85 offen lds

.Lkv_k_body_ctx:
	v_lshlrev_b32_e32 v132, s84, v130
	v_lshl_add_u32 v132, v131, 1, v132
	s_lshl_b32 s58, 16, s84
	s_mul_i32 s59, s58, 5
	v_cvt_pk_bf16_f32 v136, v126, v127
	v_cvt_pk_bf16_f32 v137, v128, v129
	global_store_dwordx2 v132, v[136:137], s[6:7] offset:0
	global_store_dwordx4 v133, v[126:129], s[8:9] offset:0
	v_cvt_pk_bf16_f32 v138, v122, v123
	v_cvt_pk_bf16_f32 v139, v124, v125
	global_store_dwordx2 v132, v[138:139], s[6:7] offset:32
	global_store_dwordx4 v133, v[122:125], s[8:9] offset:64
	v_cvt_pk_bf16_f32 v140, v94, v95
	v_cvt_pk_bf16_f32 v141, v96, v97
	global_store_dwordx2 v132, v[140:141], s[6:7] offset:256
	global_store_dwordx4 v133, v[94:97], s[8:9] offset:512
	v_cvt_pk_bf16_f32 v142, v90, v91
	v_cvt_pk_bf16_f32 v143, v92, v93
	global_store_dwordx2 v132, v[142:143], s[6:7] offset:288
	global_store_dwordx4 v133, v[90:93], s[8:9] offset:576
	s_add_u32 s6, s6, s58
	s_addc_u32 s7, s7, 0
	s_add_u32 s8, s8, s70
	s_addc_u32 s9, s9, 0
	v_cvt_pk_bf16_f32 v144, v118, v119
	v_cvt_pk_bf16_f32 v145, v120, v121
	global_store_dwordx2 v132, v[144:145], s[6:7] offset:0
	global_store_dwordx4 v133, v[118:121], s[8:9] offset:0
	v_cvt_pk_bf16_f32 v146, v114, v115
	v_cvt_pk_bf16_f32 v147, v116, v117
	global_store_dwordx2 v132, v[146:147], s[6:7] offset:32
	global_store_dwordx4 v133, v[114:117], s[8:9] offset:64
	v_cvt_pk_bf16_f32 v148, v86, v87
	v_cvt_pk_bf16_f32 v149, v88, v89
	global_store_dwordx2 v132, v[148:149], s[6:7] offset:256
	global_store_dwordx4 v133, v[86:89], s[8:9] offset:512
	v_cvt_pk_bf16_f32 v150, v82, v83
	v_cvt_pk_bf16_f32 v151, v84, v85
	global_store_dwordx2 v132, v[150:151], s[6:7] offset:288
	global_store_dwordx4 v133, v[82:85], s[8:9] offset:576
	s_add_u32 s6, s6, s58
	s_addc_u32 s7, s7, 0
	s_add_u32 s8, s8, s70
	s_addc_u32 s9, s9, 0
	v_cvt_pk_bf16_f32 v152, v110, v111
	v_cvt_pk_bf16_f32 v153, v112, v113
	global_store_dwordx2 v132, v[152:153], s[6:7] offset:0
	global_store_dwordx4 v133, v[110:113], s[8:9] offset:0
	v_cvt_pk_bf16_f32 v154, v106, v107
	v_cvt_pk_bf16_f32 v155, v108, v109
	global_store_dwordx2 v132, v[154:155], s[6:7] offset:32
	global_store_dwordx4 v133, v[106:109], s[8:9] offset:64
	v_cvt_pk_bf16_f32 v156, v78, v79
	v_cvt_pk_bf16_f32 v157, v80, v81
	global_store_dwordx2 v132, v[156:157], s[6:7] offset:256
	global_store_dwordx4 v133, v[78:81], s[8:9] offset:512
	v_cvt_pk_bf16_f32 v158, v74, v75
	v_cvt_pk_bf16_f32 v159, v76, v77
	global_store_dwordx2 v132, v[158:159], s[6:7] offset:288
	global_store_dwordx4 v133, v[74:77], s[8:9] offset:576
	s_add_u32 s6, s6, s58
	s_addc_u32 s7, s7, 0
	s_add_u32 s8, s8, s70
	s_addc_u32 s9, s9, 0
	v_cvt_pk_bf16_f32 v160, v102, v103
	v_cvt_pk_bf16_f32 v161, v104, v105
	global_store_dwordx2 v132, v[160:161], s[6:7] offset:0
	global_store_dwordx4 v133, v[102:105], s[8:9] offset:0
	v_cvt_pk_bf16_f32 v162, v98, v99
	v_cvt_pk_bf16_f32 v163, v100, v101
	global_store_dwordx2 v132, v[162:163], s[6:7] offset:32
	global_store_dwordx4 v133, v[98:101], s[8:9] offset:64
	v_cvt_pk_bf16_f32 v164, v70, v71
	v_cvt_pk_bf16_f32 v165, v72, v73
	global_store_dwordx2 v132, v[164:165], s[6:7] offset:256
	global_store_dwordx4 v133, v[70:73], s[8:9] offset:512
	v_cvt_pk_bf16_f32 v166, v66, v67
	v_cvt_pk_bf16_f32 v167, v68, v69
	global_store_dwordx2 v132, v[166:167], s[6:7] offset:288
	global_store_dwordx4 v133, v[66:69], s[8:9] offset:576
	s_add_u32 s6, s6, s59
	s_addc_u32 s7, s7, 0
	s_add_u32 s8, s8, s71
	s_addc_u32 s9, s9, 0
	v_cvt_pk_bf16_f32 v136, v62, v63
	v_cvt_pk_bf16_f32 v137, v64, v65
	global_store_dwordx2 v132, v[136:137], s[6:7] offset:0
	global_store_dwordx4 v133, v[62:65], s[8:9] offset:0
	v_cvt_pk_bf16_f32 v138, v58, v59
	v_cvt_pk_bf16_f32 v139, v60, v61
	global_store_dwordx2 v132, v[138:139], s[6:7] offset:32
	global_store_dwordx4 v133, v[58:61], s[8:9] offset:64
	v_cvt_pk_bf16_f32 v140, v30, v31
	v_cvt_pk_bf16_f32 v141, v32, v33
	global_store_dwordx2 v132, v[140:141], s[6:7] offset:256
	global_store_dwordx4 v133, v[30:33], s[8:9] offset:512
	v_cvt_pk_bf16_f32 v142, v26, v27
	v_cvt_pk_bf16_f32 v143, v28, v29
	global_store_dwordx2 v132, v[142:143], s[6:7] offset:288
	global_store_dwordx4 v133, v[26:29], s[8:9] offset:576
	s_add_u32 s6, s6, s58
	s_addc_u32 s7, s7, 0
	s_add_u32 s8, s8, s70
	s_addc_u32 s9, s9, 0
	v_cvt_pk_bf16_f32 v144, v54, v55
	v_cvt_pk_bf16_f32 v145, v56, v57
	global_store_dwordx2 v132, v[144:145], s[6:7] offset:0
	global_store_dwordx4 v133, v[54:57], s[8:9] offset:0
	v_cvt_pk_bf16_f32 v146, v50, v51
	v_cvt_pk_bf16_f32 v147, v52, v53
	global_store_dwordx2 v132, v[146:147], s[6:7] offset:32
	global_store_dwordx4 v133, v[50:53], s[8:9] offset:64
	v_cvt_pk_bf16_f32 v148, v22, v23
	v_cvt_pk_bf16_f32 v149, v24, v25
	global_store_dwordx2 v132, v[148:149], s[6:7] offset:256
	global_store_dwordx4 v133, v[22:25], s[8:9] offset:512
	v_cvt_pk_bf16_f32 v150, v18, v19
	v_cvt_pk_bf16_f32 v151, v20, v21
	global_store_dwordx2 v132, v[150:151], s[6:7] offset:288
	global_store_dwordx4 v133, v[18:21], s[8:9] offset:576
	s_add_u32 s6, s6, s58
	s_addc_u32 s7, s7, 0
	s_add_u32 s8, s8, s70
	s_addc_u32 s9, s9, 0
	v_cvt_pk_bf16_f32 v152, v46, v47
	v_cvt_pk_bf16_f32 v153, v48, v49
	global_store_dwordx2 v132, v[152:153], s[6:7] offset:0
	global_store_dwordx4 v133, v[46:49], s[8:9] offset:0
	v_cvt_pk_bf16_f32 v154, v42, v43
	v_cvt_pk_bf16_f32 v155, v44, v45
	global_store_dwordx2 v132, v[154:155], s[6:7] offset:32
	global_store_dwordx4 v133, v[42:45], s[8:9] offset:64
	v_cvt_pk_bf16_f32 v156, v14, v15
	v_cvt_pk_bf16_f32 v157, v16, v17
	global_store_dwordx2 v132, v[156:157], s[6:7] offset:256
	global_store_dwordx4 v133, v[14:17], s[8:9] offset:512
	v_cvt_pk_bf16_f32 v158, v10, v11
	v_cvt_pk_bf16_f32 v159, v12, v13
	global_store_dwordx2 v132, v[158:159], s[6:7] offset:288
	global_store_dwordx4 v133, v[10:13], s[8:9] offset:576
	s_add_u32 s6, s6, s58
	s_addc_u32 s7, s7, 0
	s_add_u32 s8, s8, s70
	s_addc_u32 s9, s9, 0
	v_cvt_pk_bf16_f32 v160, v38, v39
	v_cvt_pk_bf16_f32 v161, v40, v41
	global_store_dwordx2 v132, v[160:161], s[6:7] offset:0
	global_store_dwordx4 v133, v[38:41], s[8:9] offset:0
	v_cvt_pk_bf16_f32 v162, v34, v35
	v_cvt_pk_bf16_f32 v163, v36, v37
	global_store_dwordx2 v132, v[162:163], s[6:7] offset:32
	global_store_dwordx4 v133, v[34:37], s[8:9] offset:64
	v_cvt_pk_bf16_f32 v164, v6, v7
	v_cvt_pk_bf16_f32 v165, v8, v9
	global_store_dwordx2 v132, v[164:165], s[6:7] offset:256
	global_store_dwordx4 v133, v[6:9], s[8:9] offset:512
	v_cvt_pk_bf16_f32 v166, v2, v3
	v_cvt_pk_bf16_f32 v167, v4, v5
	global_store_dwordx2 v132, v[166:167], s[6:7] offset:288
	global_store_dwordx4 v133, v[2:5], s[8:9] offset:576
	s_branch .LBB0_247
.Lkv_k_body_lat:
	v_lshlrev_b32_e32 v132, s84, v130
	v_lshl_add_u32 v132, v131, 1, v132
	s_lshl_b32 s58, 16, s84
	s_mul_i32 s59, s58, 5
	v_cvt_pk_bf16_f32 v136, v126, v127
	v_cvt_pk_bf16_f32 v137, v128, v129
	global_store_dwordx2 v132, v[136:137], s[6:7] offset:0
	v_cvt_pk_bf16_f32 v138, v122, v123
	v_cvt_pk_bf16_f32 v139, v124, v125
	global_store_dwordx2 v132, v[138:139], s[6:7] offset:32
	v_cvt_pk_bf16_f32 v140, v94, v95
	v_cvt_pk_bf16_f32 v141, v96, v97
	global_store_dwordx2 v132, v[140:141], s[6:7] offset:256
	v_cvt_pk_bf16_f32 v142, v90, v91
	v_cvt_pk_bf16_f32 v143, v92, v93
	global_store_dwordx2 v132, v[142:143], s[6:7] offset:288
	s_add_u32 s6, s6, s58
	s_addc_u32 s7, s7, 0
	v_cvt_pk_bf16_f32 v144, v118, v119
	v_cvt_pk_bf16_f32 v145, v120, v121
	global_store_dwordx2 v132, v[144:145], s[6:7] offset:0
	v_cvt_pk_bf16_f32 v146, v114, v115
	v_cvt_pk_bf16_f32 v147, v116, v117
	global_store_dwordx2 v132, v[146:147], s[6:7] offset:32
	v_cvt_pk_bf16_f32 v148, v86, v87
	v_cvt_pk_bf16_f32 v149, v88, v89
	global_store_dwordx2 v132, v[148:149], s[6:7] offset:256
	v_cvt_pk_bf16_f32 v150, v82, v83
	v_cvt_pk_bf16_f32 v151, v84, v85
	global_store_dwordx2 v132, v[150:151], s[6:7] offset:288
	s_add_u32 s6, s6, s58
	s_addc_u32 s7, s7, 0
	v_cvt_pk_bf16_f32 v152, v110, v111
	v_cvt_pk_bf16_f32 v153, v112, v113
	global_store_dwordx2 v132, v[152:153], s[6:7] offset:0
	v_cvt_pk_bf16_f32 v154, v106, v107
	v_cvt_pk_bf16_f32 v155, v108, v109
	global_store_dwordx2 v132, v[154:155], s[6:7] offset:32
	v_cvt_pk_bf16_f32 v156, v78, v79
	v_cvt_pk_bf16_f32 v157, v80, v81
	global_store_dwordx2 v132, v[156:157], s[6:7] offset:256
	v_cvt_pk_bf16_f32 v158, v74, v75
	v_cvt_pk_bf16_f32 v159, v76, v77
	global_store_dwordx2 v132, v[158:159], s[6:7] offset:288
	s_add_u32 s6, s6, s58
	s_addc_u32 s7, s7, 0
	v_cvt_pk_bf16_f32 v160, v102, v103
	v_cvt_pk_bf16_f32 v161, v104, v105
	global_store_dwordx2 v132, v[160:161], s[6:7] offset:0
	v_cvt_pk_bf16_f32 v162, v98, v99
	v_cvt_pk_bf16_f32 v163, v100, v101
	global_store_dwordx2 v132, v[162:163], s[6:7] offset:32
	v_cvt_pk_bf16_f32 v164, v70, v71
	v_cvt_pk_bf16_f32 v165, v72, v73
	global_store_dwordx2 v132, v[164:165], s[6:7] offset:256
	v_cvt_pk_bf16_f32 v166, v66, v67
	v_cvt_pk_bf16_f32 v167, v68, v69
	global_store_dwordx2 v132, v[166:167], s[6:7] offset:288
	s_add_u32 s6, s6, s59
	s_addc_u32 s7, s7, 0
	v_cvt_pk_bf16_f32 v136, v62, v63
	v_cvt_pk_bf16_f32 v137, v64, v65
	global_store_dwordx2 v132, v[136:137], s[6:7] offset:0
	v_cvt_pk_bf16_f32 v138, v58, v59
	v_cvt_pk_bf16_f32 v139, v60, v61
	global_store_dwordx2 v132, v[138:139], s[6:7] offset:32
	v_cvt_pk_bf16_f32 v140, v30, v31
	v_cvt_pk_bf16_f32 v141, v32, v33
	global_store_dwordx2 v132, v[140:141], s[6:7] offset:256
	v_cvt_pk_bf16_f32 v142, v26, v27
	v_cvt_pk_bf16_f32 v143, v28, v29
	global_store_dwordx2 v132, v[142:143], s[6:7] offset:288
	s_add_u32 s6, s6, s58
	s_addc_u32 s7, s7, 0
	v_cvt_pk_bf16_f32 v144, v54, v55
	v_cvt_pk_bf16_f32 v145, v56, v57
	global_store_dwordx2 v132, v[144:145], s[6:7] offset:0
	v_cvt_pk_bf16_f32 v146, v50, v51
	v_cvt_pk_bf16_f32 v147, v52, v53
	global_store_dwordx2 v132, v[146:147], s[6:7] offset:32
	v_cvt_pk_bf16_f32 v148, v22, v23
	v_cvt_pk_bf16_f32 v149, v24, v25
	global_store_dwordx2 v132, v[148:149], s[6:7] offset:256
	v_cvt_pk_bf16_f32 v150, v18, v19
	v_cvt_pk_bf16_f32 v151, v20, v21
	global_store_dwordx2 v132, v[150:151], s[6:7] offset:288
	s_add_u32 s6, s6, s58
	s_addc_u32 s7, s7, 0
	v_cvt_pk_bf16_f32 v152, v46, v47
	v_cvt_pk_bf16_f32 v153, v48, v49
	global_store_dwordx2 v132, v[152:153], s[6:7] offset:0
	v_cvt_pk_bf16_f32 v154, v42, v43
	v_cvt_pk_bf16_f32 v155, v44, v45
	global_store_dwordx2 v132, v[154:155], s[6:7] offset:32
	v_cvt_pk_bf16_f32 v156, v14, v15
	v_cvt_pk_bf16_f32 v157, v16, v17
	global_store_dwordx2 v132, v[156:157], s[6:7] offset:256
	v_cvt_pk_bf16_f32 v158, v10, v11
	v_cvt_pk_bf16_f32 v159, v12, v13
	global_store_dwordx2 v132, v[158:159], s[6:7] offset:288
	s_add_u32 s6, s6, s58
	s_addc_u32 s7, s7, 0
	v_cvt_pk_bf16_f32 v160, v38, v39
	v_cvt_pk_bf16_f32 v161, v40, v41
	global_store_dwordx2 v132, v[160:161], s[6:7] offset:0
	v_cvt_pk_bf16_f32 v162, v34, v35
	v_cvt_pk_bf16_f32 v163, v36, v37
	global_store_dwordx2 v132, v[162:163], s[6:7] offset:32
	v_cvt_pk_bf16_f32 v164, v6, v7
	v_cvt_pk_bf16_f32 v165, v8, v9
	global_store_dwordx2 v132, v[164:165], s[6:7] offset:256
	v_cvt_pk_bf16_f32 v166, v2, v3
	v_cvt_pk_bf16_f32 v167, v4, v5
	global_store_dwordx2 v132, v[166:167], s[6:7] offset:288
	s_branch .LBB0_247
